# sel score loops: key-tile load address from a per-loop precomputed base + tile<<15 (1 VALU instead of 4) and the second score-plane write base kept in a register (no per-write add)
# speedup vs baseline: 1.0025x; 1.0025x over previous
.Lselq_skip:
	s_or_b64 exec, exec, s[98:99]
	s_mov_b32 s8, 6
	v_mov_b32_e32 v99, v180
	v_mov_b32_e32 v244, v102
	v_ashrrev_i32_e32 v245, 31, v102
	v_lshlrev_b64 v[244:245], 7, v[244:245]
	v_lshl_add_u64 v[244:245], v[100:101], 0, v[244:245]
	s_mov_b32 s99, 0
	v_add_u32_e32 v246, 0x10000, v99
	s_branch .LBB0_820
.LBB0_819:
	s_add_i32 s8, s8, 4
	s_cmp_lt_i32 s9, s6
	v_add_u32_e32 v99, 0x1000, v99
	v_add_u32_e32 v246, 0x1000, v246
	s_cbranch_scc0 .LBB0_826
.LBB0_820:
	s_add_i32 s40, s8, -3
	s_min_i32 s9, s40, s7
	s_lshl_b32 s98, s9, 15
	s_waitcnt vmcnt(12)
	v_lshl_add_u64 v[60:61], v[244:245], 0, s[98:99]
	global_load_dwordx4 v[88:91], v[60:61], off
	global_load_dwordx4 v[92:95], v[60:61], off offset:1024
	global_load_dwordx4 v[56:59], v[60:61], off offset:2048
	s_nop 0
	global_load_dwordx4 v[60:63], v[60:61], off offset:3072
	v_add_u32_e32 v103, v178, v98
	s_waitcnt vmcnt(15)
	ds_write_b128 v103, v[64:67]
	s_waitcnt vmcnt(14)
	ds_write_b128 v103, v[68:71] offset:1152
	v_add_u32_e32 v107, v179, v96
	ds_read_b128 v[64:67], v107
	ds_read_b128 v[68:71], v107 offset:64
	s_waitcnt vmcnt(13)
	ds_write_b128 v103, v[32:35]
	s_waitcnt vmcnt(12)
	ds_write_b128 v103, v[36:39] offset:1152
	ds_read_b128 v[32:35], v107
	ds_read_b128 v[36:39], v107 offset:64
	s_waitcnt lgkmcnt(5)
	v_mfma_f32_16x16x32_bf16 v[108:111], v[0:3], v[64:67], 0
	v_mfma_f32_16x16x32_bf16 v[112:115], v[8:11], v[64:67], 0
	s_waitcnt lgkmcnt(4)
	v_mfma_f32_16x16x32_bf16 v[108:111], v[4:7], v[68:71], v[108:111]
	v_mfma_f32_16x16x32_bf16 v[112:115], v[12:15], v[68:71], v[112:115]
	v_mfma_f32_16x16x32_bf16 v[116:119], v[16:19], v[64:67], 0
	s_nop 5
	v_max_f32_e32 v108, 0, v108
	v_fma_f32 v120, v162, v108, 0
	v_max_f32_e32 v108, 0, v109
	v_max_f32_e32 v112, 0, v112
	v_fmac_f32_e32 v120, v163, v108
	v_fma_f32 v112, v166, v112, 0
	v_max_f32_e32 v108, 0, v113
	v_fmac_f32_e32 v112, v167, v108
	v_max_f32_e32 v108, 0, v110
	v_fmac_f32_e32 v120, v164, v108
	v_mfma_f32_16x16x32_bf16 v[64:67], v[24:27], v[64:67], 0
	v_max_f32_e32 v108, 0, v114
	v_fmac_f32_e32 v112, v168, v108
	v_max_f32_e32 v108, 0, v111
	v_fmac_f32_e32 v120, v165, v108
	v_mfma_f32_16x16x32_bf16 v[64:67], v[28:31], v[68:71], v[64:67]
	v_max_f32_e32 v113, 0, v115
	v_fmac_f32_e32 v112, v169, v113
	v_add_f32_e32 v112, v120, v112
	v_mfma_f32_16x16x32_bf16 v[108:111], v[20:23], v[68:71], v[116:119]
	ds_write_b32 v99, v112
	s_nop 2
	v_max_f32_e32 v64, 0, v64
	v_fma_f32 v64, v174, v64, 0
	s_nop 1
	v_max_f32_e32 v68, 0, v108
	v_max_f32_e32 v65, 0, v65
	v_fma_f32 v68, v170, v68, 0
	v_max_f32_e32 v69, 0, v109
	v_fmac_f32_e32 v64, v175, v65
	v_fmac_f32_e32 v68, v171, v69
	v_max_f32_e32 v65, 0, v110
	v_fmac_f32_e32 v68, v172, v65
	v_max_f32_e32 v65, 0, v66
	v_fmac_f32_e32 v64, v176, v65
	v_max_f32_e32 v65, 0, v111
	v_fmac_f32_e32 v68, v173, v65
	v_max_f32_e32 v65, 0, v67
	v_fmac_f32_e32 v64, v177, v65
	v_add_f32_e32 v64, v68, v64
	ds_write_b32 v246, v64
	s_waitcnt lgkmcnt(3)
	v_mfma_f32_16x16x32_bf16 v[64:67], v[0:3], v[32:35], 0
	v_mfma_f32_16x16x32_bf16 v[68:71], v[8:11], v[32:35], 0
	s_waitcnt lgkmcnt(2)
	v_mfma_f32_16x16x32_bf16 v[64:67], v[4:7], v[36:39], v[64:67]
	v_mfma_f32_16x16x32_bf16 v[68:71], v[12:15], v[36:39], v[68:71]
	v_mfma_f32_16x16x32_bf16 v[108:111], v[16:19], v[32:35], 0
	s_nop 5
	v_max_f32_e32 v64, 0, v64
	v_fma_f32 v112, v162, v64, 0
	v_max_f32_e32 v64, 0, v68
	v_fma_f32 v68, v166, v64, 0
	v_max_f32_e32 v64, 0, v65
	v_fmac_f32_e32 v112, v163, v64
	v_max_f32_e32 v64, 0, v69
	v_fmac_f32_e32 v68, v167, v64
	v_max_f32_e32 v64, 0, v66
	v_fmac_f32_e32 v112, v164, v64
	v_mfma_f32_16x16x32_bf16 v[32:35], v[24:27], v[32:35], 0
	v_max_f32_e32 v64, 0, v70
	v_fmac_f32_e32 v68, v168, v64
	v_max_f32_e32 v64, 0, v67
	v_fmac_f32_e32 v112, v165, v64
	v_mfma_f32_16x16x32_bf16 v[32:35], v[28:31], v[36:39], v[32:35]
	v_max_f32_e32 v69, 0, v71
	v_fmac_f32_e32 v68, v169, v69
	v_add_f32_e32 v68, v112, v68
	v_mfma_f32_16x16x32_bf16 v[64:67], v[20:23], v[36:39], v[108:111]
	ds_write_b32 v99, v68 offset:64
	s_nop 2
	v_max_f32_e32 v32, 0, v32
	v_fma_f32 v32, v174, v32, 0
	s_nop 1
	v_max_f32_e32 v36, 0, v64
	v_max_f32_e32 v33, 0, v33
	v_fma_f32 v36, v170, v36, 0
	v_max_f32_e32 v37, 0, v65
	v_fmac_f32_e32 v32, v175, v33
	v_fmac_f32_e32 v36, v171, v37
	v_max_f32_e32 v33, 0, v66
	v_fmac_f32_e32 v36, v172, v33
	v_max_f32_e32 v33, 0, v34
	v_fmac_f32_e32 v32, v176, v33
	v_max_f32_e32 v33, 0, v67
	v_fmac_f32_e32 v36, v173, v33
	v_max_f32_e32 v33, 0, v35
	v_fmac_f32_e32 v32, v177, v33
	v_add_f32_e32 v32, v36, v32
	ds_write_b32 v246, v32 offset:64
	s_add_i32 s9, s8, -2
	s_min_i32 s57, s9, s7
	s_lshl_b32 s98, s57, 15
	v_lshl_add_u64 v[36:37], v[244:245], 0, s[98:99]
	global_load_dwordx4 v[64:67], v[36:37], off
	global_load_dwordx4 v[68:71], v[36:37], off offset:1024
	global_load_dwordx4 v[32:35], v[36:37], off offset:2048
	s_nop 0
	global_load_dwordx4 v[36:39], v[36:37], off offset:3072
	s_add_i32 s57, s8, -5
	s_cmp_ge_i32 s57, s6
	s_cbranch_scc1 .LBB0_822
	s_waitcnt vmcnt(15)
	ds_write_b128 v103, v[72:75]
	s_waitcnt vmcnt(14)
	ds_write_b128 v103, v[76:79] offset:1152
	ds_read_b128 v[72:75], v107
	ds_read_b128 v[76:79], v107 offset:64
	s_waitcnt vmcnt(13)
	ds_write_b128 v103, v[40:43]
	s_waitcnt vmcnt(12)
	ds_write_b128 v103, v[44:47] offset:1152
	ds_read_b128 v[40:43], v107
	ds_read_b128 v[44:47], v107 offset:64
	s_waitcnt lgkmcnt(5)
	v_mfma_f32_16x16x32_bf16 v[108:111], v[0:3], v[72:75], 0
	v_mfma_f32_16x16x32_bf16 v[112:115], v[8:11], v[72:75], 0
	s_waitcnt lgkmcnt(4)
	v_mfma_f32_16x16x32_bf16 v[108:111], v[4:7], v[76:79], v[108:111]
	v_mfma_f32_16x16x32_bf16 v[112:115], v[12:15], v[76:79], v[112:115]
	v_mfma_f32_16x16x32_bf16 v[116:119], v[16:19], v[72:75], 0
	s_nop 5
	v_max_f32_e32 v108, 0, v108
	v_fma_f32 v120, v162, v108, 0
	v_max_f32_e32 v108, 0, v109
	v_max_f32_e32 v112, 0, v112
	v_fmac_f32_e32 v120, v163, v108
	v_fma_f32 v112, v166, v112, 0
	v_max_f32_e32 v108, 0, v113
	v_fmac_f32_e32 v112, v167, v108
	v_max_f32_e32 v108, 0, v110
	v_fmac_f32_e32 v120, v164, v108
	v_mfma_f32_16x16x32_bf16 v[72:75], v[24:27], v[72:75], 0
	v_max_f32_e32 v108, 0, v114
	v_fmac_f32_e32 v112, v168, v108
	v_max_f32_e32 v108, 0, v111
	v_fmac_f32_e32 v120, v165, v108
	v_mfma_f32_16x16x32_bf16 v[72:75], v[28:31], v[76:79], v[72:75]
	v_max_f32_e32 v113, 0, v115
	v_fmac_f32_e32 v112, v169, v113
	v_add_f32_e32 v112, v120, v112
	v_mfma_f32_16x16x32_bf16 v[108:111], v[20:23], v[76:79], v[116:119]
	ds_write_b32 v99, v112 offset:1024
	s_nop 2
	v_max_f32_e32 v72, 0, v72
	v_fma_f32 v72, v174, v72, 0
	s_nop 1
	v_max_f32_e32 v76, 0, v108
	v_max_f32_e32 v73, 0, v73
	v_fma_f32 v76, v170, v76, 0
	v_max_f32_e32 v77, 0, v109
	v_fmac_f32_e32 v72, v175, v73
	v_fmac_f32_e32 v76, v171, v77
	v_max_f32_e32 v73, 0, v110
	v_fmac_f32_e32 v76, v172, v73
	v_max_f32_e32 v73, 0, v74
	v_fmac_f32_e32 v72, v176, v73
	v_max_f32_e32 v73, 0, v111
	v_fmac_f32_e32 v76, v173, v73
	v_max_f32_e32 v73, 0, v75
	v_fmac_f32_e32 v72, v177, v73
	v_add_f32_e32 v72, v76, v72
	ds_write_b32 v246, v72 offset:1024
	s_waitcnt lgkmcnt(3)
	v_mfma_f32_16x16x32_bf16 v[72:75], v[0:3], v[40:43], 0
	v_mfma_f32_16x16x32_bf16 v[76:79], v[8:11], v[40:43], 0
	s_waitcnt lgkmcnt(2)
	v_mfma_f32_16x16x32_bf16 v[72:75], v[4:7], v[44:47], v[72:75]
	v_mfma_f32_16x16x32_bf16 v[76:79], v[12:15], v[44:47], v[76:79]
	v_mfma_f32_16x16x32_bf16 v[108:111], v[16:19], v[40:43], 0
	s_nop 5
	v_max_f32_e32 v72, 0, v72
	v_fma_f32 v112, v162, v72, 0
	v_max_f32_e32 v72, 0, v76
	v_fma_f32 v76, v166, v72, 0
	v_max_f32_e32 v72, 0, v73
	v_fmac_f32_e32 v112, v163, v72
	v_max_f32_e32 v72, 0, v77
	v_fmac_f32_e32 v76, v167, v72
	v_max_f32_e32 v72, 0, v74
	v_fmac_f32_e32 v112, v164, v72
	v_mfma_f32_16x16x32_bf16 v[40:43], v[24:27], v[40:43], 0
	v_max_f32_e32 v72, 0, v78
	v_fmac_f32_e32 v76, v168, v72
	v_max_f32_e32 v72, 0, v75
	v_fmac_f32_e32 v112, v165, v72
	v_mfma_f32_16x16x32_bf16 v[40:43], v[28:31], v[44:47], v[40:43]
	v_max_f32_e32 v77, 0, v79
	v_fmac_f32_e32 v76, v169, v77
	v_add_f32_e32 v76, v112, v76
	v_mfma_f32_16x16x32_bf16 v[72:75], v[20:23], v[44:47], v[108:111]
	ds_write_b32 v99, v76 offset:1088
	s_nop 2
	v_max_f32_e32 v40, 0, v40
	v_fma_f32 v40, v174, v40, 0
	s_nop 1
	v_max_f32_e32 v44, 0, v72
	v_max_f32_e32 v41, 0, v41
	v_fma_f32 v44, v170, v44, 0
	v_max_f32_e32 v45, 0, v73
	v_fmac_f32_e32 v40, v175, v41
	v_fmac_f32_e32 v44, v171, v45
	v_max_f32_e32 v41, 0, v74
	v_fmac_f32_e32 v44, v172, v41
	v_max_f32_e32 v41, 0, v42
	v_fmac_f32_e32 v40, v176, v41
	v_max_f32_e32 v41, 0, v75
	v_fmac_f32_e32 v44, v173, v41
	v_max_f32_e32 v41, 0, v43
	v_fmac_f32_e32 v40, v177, v41
	v_add_f32_e32 v40, v44, v40
	ds_write_b32 v246, v40 offset:1088
.LBB0_822:
	s_add_i32 s57, s8, -1
	s_min_i32 s57, s57, s7
	s_lshl_b32 s98, s57, 15
	s_waitcnt vmcnt(12)
	v_lshl_add_u64 v[44:45], v[244:245], 0, s[98:99]
	global_load_dwordx4 v[72:75], v[44:45], off
	global_load_dwordx4 v[76:79], v[44:45], off offset:1024
	global_load_dwordx4 v[40:43], v[44:45], off offset:2048
	s_nop 0
	global_load_dwordx4 v[44:47], v[44:45], off offset:3072
	s_add_i32 s57, s8, -4
	s_cmp_ge_i32 s57, s6
	s_cbranch_scc1 .LBB0_824
	s_waitcnt vmcnt(15)
	ds_write_b128 v103, v[80:83]
	s_waitcnt vmcnt(14)
	ds_write_b128 v103, v[84:87] offset:1152
	ds_read_b128 v[80:83], v107
	ds_read_b128 v[84:87], v107 offset:64
	s_waitcnt vmcnt(13)
	ds_write_b128 v103, v[48:51]
	s_waitcnt vmcnt(12)
	ds_write_b128 v103, v[52:55] offset:1152
	ds_read_b128 v[48:51], v107
	ds_read_b128 v[52:55], v107 offset:64
	s_waitcnt lgkmcnt(5)
	v_mfma_f32_16x16x32_bf16 v[108:111], v[0:3], v[80:83], 0
	v_mfma_f32_16x16x32_bf16 v[112:115], v[8:11], v[80:83], 0
	s_waitcnt lgkmcnt(4)
	v_mfma_f32_16x16x32_bf16 v[108:111], v[4:7], v[84:87], v[108:111]
	v_mfma_f32_16x16x32_bf16 v[112:115], v[12:15], v[84:87], v[112:115]
	v_mfma_f32_16x16x32_bf16 v[116:119], v[16:19], v[80:83], 0
	s_nop 5
	v_max_f32_e32 v108, 0, v108
	v_fma_f32 v120, v162, v108, 0
	v_max_f32_e32 v108, 0, v109
	v_max_f32_e32 v112, 0, v112
	v_fmac_f32_e32 v120, v163, v108
	v_fma_f32 v112, v166, v112, 0
	v_max_f32_e32 v108, 0, v113
	v_fmac_f32_e32 v112, v167, v108
	v_max_f32_e32 v108, 0, v110
	v_fmac_f32_e32 v120, v164, v108
	v_mfma_f32_16x16x32_bf16 v[80:83], v[24:27], v[80:83], 0
	v_max_f32_e32 v108, 0, v114
	v_fmac_f32_e32 v112, v168, v108
	v_max_f32_e32 v108, 0, v111
	v_fmac_f32_e32 v120, v165, v108
	v_mfma_f32_16x16x32_bf16 v[80:83], v[28:31], v[84:87], v[80:83]
	v_max_f32_e32 v113, 0, v115
	v_fmac_f32_e32 v112, v169, v113
	v_add_f32_e32 v112, v120, v112
	v_mfma_f32_16x16x32_bf16 v[108:111], v[20:23], v[84:87], v[116:119]
	ds_write_b32 v99, v112 offset:2048
	s_nop 2
	v_max_f32_e32 v80, 0, v80
	v_fma_f32 v80, v174, v80, 0
	s_nop 1
	v_max_f32_e32 v84, 0, v108
	v_max_f32_e32 v81, 0, v81
	v_fma_f32 v84, v170, v84, 0
	v_max_f32_e32 v85, 0, v109
	v_fmac_f32_e32 v80, v175, v81
	v_fmac_f32_e32 v84, v171, v85
	v_max_f32_e32 v81, 0, v110
	v_fmac_f32_e32 v84, v172, v81
	v_max_f32_e32 v81, 0, v82
	v_fmac_f32_e32 v80, v176, v81
	v_max_f32_e32 v81, 0, v111
	v_fmac_f32_e32 v84, v173, v81
	v_max_f32_e32 v81, 0, v83
	v_fmac_f32_e32 v80, v177, v81
	v_add_f32_e32 v80, v84, v80
	ds_write_b32 v246, v80 offset:2048
	s_waitcnt lgkmcnt(3)
	v_mfma_f32_16x16x32_bf16 v[80:83], v[0:3], v[48:51], 0
	v_mfma_f32_16x16x32_bf16 v[84:87], v[8:11], v[48:51], 0
	s_waitcnt lgkmcnt(2)
	v_mfma_f32_16x16x32_bf16 v[80:83], v[4:7], v[52:55], v[80:83]
	v_mfma_f32_16x16x32_bf16 v[84:87], v[12:15], v[52:55], v[84:87]
	v_mfma_f32_16x16x32_bf16 v[108:111], v[16:19], v[48:51], 0
	s_nop 5
	v_max_f32_e32 v80, 0, v80
	v_fma_f32 v112, v162, v80, 0
	v_max_f32_e32 v80, 0, v84
	v_fma_f32 v84, v166, v80, 0
	v_max_f32_e32 v80, 0, v81
	v_fmac_f32_e32 v112, v163, v80
	v_max_f32_e32 v80, 0, v85
	v_fmac_f32_e32 v84, v167, v80
	v_max_f32_e32 v80, 0, v82
	v_fmac_f32_e32 v112, v164, v80
	v_mfma_f32_16x16x32_bf16 v[48:51], v[24:27], v[48:51], 0
	v_max_f32_e32 v80, 0, v86
	v_fmac_f32_e32 v84, v168, v80
	v_max_f32_e32 v80, 0, v83
	v_fmac_f32_e32 v112, v165, v80
	v_mfma_f32_16x16x32_bf16 v[48:51], v[28:31], v[52:55], v[48:51]
	v_max_f32_e32 v85, 0, v87
	v_fmac_f32_e32 v84, v169, v85
	v_add_f32_e32 v84, v112, v84
	v_mfma_f32_16x16x32_bf16 v[80:83], v[20:23], v[52:55], v[108:111]
	ds_write_b32 v99, v84 offset:2112
	s_nop 2
	v_max_f32_e32 v48, 0, v48
	v_fma_f32 v48, v174, v48, 0
	s_nop 1
	v_max_f32_e32 v52, 0, v80
	v_max_f32_e32 v49, 0, v49
	v_fma_f32 v52, v170, v52, 0
	v_max_f32_e32 v53, 0, v81
	v_fmac_f32_e32 v48, v175, v49
	v_fmac_f32_e32 v52, v171, v53
	v_max_f32_e32 v49, 0, v82
	v_fmac_f32_e32 v52, v172, v49
	v_max_f32_e32 v49, 0, v50
	v_fmac_f32_e32 v48, v176, v49
	v_max_f32_e32 v49, 0, v83
	v_fmac_f32_e32 v52, v173, v49
	v_max_f32_e32 v49, 0, v51
	v_fmac_f32_e32 v48, v177, v49
	v_add_f32_e32 v48, v52, v48
	ds_write_b32 v246, v48 offset:2112
.LBB0_824:
	s_min_i32 s57, s8, s7
	s_lshl_b32 s98, s57, 15
	s_cmp_ge_i32 s40, s6
	s_waitcnt vmcnt(12)
	v_lshl_add_u64 v[52:53], v[244:245], 0, s[98:99]
	global_load_dwordx4 v[80:83], v[52:53], off
	global_load_dwordx4 v[84:87], v[52:53], off offset:1024
	global_load_dwordx4 v[48:51], v[52:53], off offset:2048
	s_nop 0
	global_load_dwordx4 v[52:55], v[52:53], off offset:3072
	s_cbranch_scc1 .LBB0_819
	s_waitcnt vmcnt(15)
	ds_write_b128 v103, v[88:91]
	s_waitcnt vmcnt(14)
	ds_write_b128 v103, v[92:95] offset:1152
	ds_read_b128 v[88:91], v107
	ds_read_b128 v[92:95], v107 offset:64
	s_waitcnt vmcnt(13)
	ds_write_b128 v103, v[56:59]
	s_waitcnt vmcnt(12)
	ds_write_b128 v103, v[60:63] offset:1152
	ds_read_b128 v[56:59], v107
	ds_read_b128 v[60:63], v107 offset:64
	s_waitcnt lgkmcnt(5)
	v_mfma_f32_16x16x32_bf16 v[108:111], v[0:3], v[88:91], 0
	v_mfma_f32_16x16x32_bf16 v[112:115], v[8:11], v[88:91], 0
	s_waitcnt lgkmcnt(4)
	v_mfma_f32_16x16x32_bf16 v[108:111], v[4:7], v[92:95], v[108:111]
	v_mfma_f32_16x16x32_bf16 v[112:115], v[12:15], v[92:95], v[112:115]
	v_mfma_f32_16x16x32_bf16 v[116:119], v[16:19], v[88:91], 0
	s_nop 5
	v_max_f32_e32 v108, 0, v108
	v_fma_f32 v120, v162, v108, 0
	v_max_f32_e32 v108, 0, v109
	v_max_f32_e32 v112, 0, v112
	v_fmac_f32_e32 v120, v163, v108
	v_fma_f32 v112, v166, v112, 0
	v_max_f32_e32 v108, 0, v113
	v_fmac_f32_e32 v112, v167, v108
	v_max_f32_e32 v108, 0, v110
	v_fmac_f32_e32 v120, v164, v108
	v_mfma_f32_16x16x32_bf16 v[88:91], v[24:27], v[88:91], 0
	v_max_f32_e32 v108, 0, v114
	v_fmac_f32_e32 v112, v168, v108
	v_max_f32_e32 v108, 0, v111
	v_fmac_f32_e32 v120, v165, v108
	v_mfma_f32_16x16x32_bf16 v[88:91], v[28:31], v[92:95], v[88:91]
	v_max_f32_e32 v113, 0, v115
	v_fmac_f32_e32 v112, v169, v113
	v_add_f32_e32 v112, v120, v112
	v_mfma_f32_16x16x32_bf16 v[108:111], v[20:23], v[92:95], v[116:119]
	ds_write_b32 v99, v112 offset:3072
	s_nop 2
	v_max_f32_e32 v88, 0, v88
	v_fma_f32 v88, v174, v88, 0
	s_nop 1
	v_max_f32_e32 v92, 0, v108
	v_max_f32_e32 v89, 0, v89
	v_fma_f32 v92, v170, v92, 0
	v_max_f32_e32 v93, 0, v109
	v_fmac_f32_e32 v88, v175, v89
	v_fmac_f32_e32 v92, v171, v93
	v_max_f32_e32 v89, 0, v110
	v_fmac_f32_e32 v92, v172, v89
	v_max_f32_e32 v89, 0, v90
	v_fmac_f32_e32 v88, v176, v89
	v_max_f32_e32 v89, 0, v111
	v_fmac_f32_e32 v92, v173, v89
	v_max_f32_e32 v89, 0, v91
	v_fmac_f32_e32 v88, v177, v89
	v_add_f32_e32 v88, v92, v88
	ds_write_b32 v246, v88 offset:3072
	s_waitcnt lgkmcnt(3)
	v_mfma_f32_16x16x32_bf16 v[88:91], v[0:3], v[56:59], 0
	v_mfma_f32_16x16x32_bf16 v[92:95], v[8:11], v[56:59], 0
	s_waitcnt lgkmcnt(2)
	v_mfma_f32_16x16x32_bf16 v[88:91], v[4:7], v[60:63], v[88:91]
	v_mfma_f32_16x16x32_bf16 v[92:95], v[12:15], v[60:63], v[92:95]
	v_mfma_f32_16x16x32_bf16 v[108:111], v[16:19], v[56:59], 0
	s_nop 5
	v_max_f32_e32 v88, 0, v88
	v_fma_f32 v103, v162, v88, 0
	v_max_f32_e32 v88, 0, v92
	v_fma_f32 v92, v166, v88, 0
	v_max_f32_e32 v88, 0, v89
	v_fmac_f32_e32 v103, v163, v88
	v_max_f32_e32 v88, 0, v93
	v_fmac_f32_e32 v92, v167, v88
	v_max_f32_e32 v88, 0, v90
	v_fmac_f32_e32 v103, v164, v88
	v_mfma_f32_16x16x32_bf16 v[56:59], v[24:27], v[56:59], 0
	v_max_f32_e32 v88, 0, v94
	v_fmac_f32_e32 v92, v168, v88
	v_max_f32_e32 v88, 0, v91
	v_fmac_f32_e32 v103, v165, v88
	v_mfma_f32_16x16x32_bf16 v[56:59], v[28:31], v[60:63], v[56:59]
	v_max_f32_e32 v93, 0, v95
	v_fmac_f32_e32 v92, v169, v93
	v_add_f32_e32 v92, v103, v92
	v_mfma_f32_16x16x32_bf16 v[88:91], v[20:23], v[60:63], v[108:111]
	ds_write_b32 v99, v92 offset:3136
	s_nop 2
	v_max_f32_e32 v56, 0, v56
	v_fma_f32 v56, v174, v56, 0
	s_nop 1
	v_max_f32_e32 v60, 0, v88
	v_max_f32_e32 v57, 0, v57
	v_fma_f32 v60, v170, v60, 0
	v_max_f32_e32 v61, 0, v89
	v_fmac_f32_e32 v56, v175, v57
	v_fmac_f32_e32 v60, v171, v61
	v_max_f32_e32 v57, 0, v90
	v_fmac_f32_e32 v60, v172, v57
	v_max_f32_e32 v57, 0, v58
	v_fmac_f32_e32 v56, v176, v57
	v_max_f32_e32 v57, 0, v91
	v_fmac_f32_e32 v60, v173, v57
	v_max_f32_e32 v57, 0, v59
	v_fmac_f32_e32 v56, v177, v57
	v_add_f32_e32 v56, v60, v56
	ds_write_b32 v246, v56 offset:3136
	s_branch .LBB0_819

.LBB0_830:
	s_waitcnt vmcnt(14)
	v_mov_b32_e32 v92, 0
	s_cmpk_lt_u32 s19, 0x1001
	v_mov_b32_e32 v90, 0
	v_mov_b32_e32 v88, 0
	s_waitcnt vmcnt(2)
	v_mov_b32_e32 v86, 0
	v_mov_b32_e32 v84, 0
	v_mov_b32_e32 v82, 0
	v_mov_b32_e32 v80, 0
	v_mov_b32_e32 v78, 0
	v_mov_b32_e32 v76, 0
	v_mov_b32_e32 v74, 0
	v_mov_b32_e32 v72, 0
	v_mov_b32_e32 v70, 0
	v_mov_b32_e32 v68, 0
	v_mov_b32_e32 v66, 0
	v_mov_b32_e32 v64, 0
	v_mov_b32_e32 v62, 0
	v_mov_b32_e32 v60, 0
	v_mov_b32_e32 v58, 0
	v_mov_b32_e32 v56, 0
	s_waitcnt vmcnt(0)
	v_mov_b32_e32 v54, 0
	v_mov_b32_e32 v52, 0
	v_mov_b32_e32 v50, 0
	v_mov_b32_e32 v48, 0
	v_mov_b32_e32 v46, 0
	v_mov_b32_e32 v34, 0
	v_mov_b32_e32 v36, 0
	v_mov_b32_e32 v38, 0
	v_mov_b32_e32 v40, 0
	v_mov_b32_e32 v42, 0
	v_mov_b32_e32 v45, 0
	v_mov_b32_e32 v47, 0
	v_mov_b32_e32 v49, 0
	v_mov_b32_e32 v51, 0
	v_mov_b32_e32 v53, 0
	v_mov_b32_e32 v55, 0
	v_mov_b32_e32 v57, 0
	v_mov_b32_e32 v59, 0
	v_mov_b32_e32 v61, 0
	v_mov_b32_e32 v63, 0
	v_mov_b32_e32 v65, 0
	v_mov_b32_e32 v67, 0
	v_mov_b32_e32 v69, 0
	v_mov_b32_e32 v71, 0
	v_mov_b32_e32 v73, 0
	v_mov_b32_e32 v75, 0
	v_mov_b32_e32 v77, 0
	v_mov_b32_e32 v79, 0
	v_mov_b32_e32 v81, 0
	v_mov_b32_e32 v83, 0
	v_mov_b32_e32 v85, 0
	v_mov_b32_e32 v87, 0
	v_mov_b32_e32 v89, 0
	v_mov_b32_e32 v91, 0
	v_mov_b32_e32 v93, 0
	v_mov_b32_e32 v94, 0
	v_mov_b32_e32 v95, 0
	v_mov_b32_e32 v32, 0
	v_mov_b32_e32 v33, 0
	v_mov_b32_e32 v35, 0
	v_mov_b32_e32 v37, 0
	v_mov_b32_e32 v39, 0
	v_mov_b32_e32 v41, 0
	v_mov_b32_e32 v43, 0
	v_mov_b32_e32 v44, 0
	s_cbranch_scc1 .LBB0_843
	s_min_u32 s6, s19, 0x2000
	s_addk_i32 s6, 0xf01f
	s_lshr_b32 s6, s6, 5
	s_sub_i32 s8, s6, s12
	s_cmp_lt_i32 s8, 1
	s_barrier
	s_cbranch_scc1 .LBB0_840
	s_add_i32 s6, s8, 7
	s_lshr_b32 s7, s6, 29
	s_add_i32 s6, s6, s7
	s_ashr_i32 s6, s6, 3
	s_add_i32 s7, s6, -1
	s_add_i32 s9, s12, 0x80
	s_lshl_b32 s40, s7, 3
	s_cmp_lt_u32 s8, 9
	s_cselect_b32 s57, s40, 8
	s_add_i32 s57, s57, s9
	s_cmp_lt_u32 s8, 17
	s_cselect_b32 s8, s40, 16
	s_add_i32 s8, s8, s9
	v_lshl_or_b32 v102, s9, 5, v191
	v_lshl_or_b32 v40, s57, 5, v191
	v_lshl_or_b32 v48, s8, 5, v191
	v_ashrrev_i32_e32 v103, 31, v102
	v_ashrrev_i32_e32 v41, 31, v40
	v_ashrrev_i32_e32 v49, 31, v48
	v_lshlrev_b64 v[32:33], 7, v[102:103]
	v_lshlrev_b64 v[40:41], 7, v[40:41]
	v_lshlrev_b64 v[48:49], 7, v[48:49]
	v_lshl_add_u64 v[36:37], v[100:101], 0, v[32:33]
	v_lshl_add_u64 v[44:45], v[100:101], 0, v[40:41]
	v_lshl_add_u64 v[52:53], v[100:101], 0, v[48:49]
	global_load_dwordx4 v[64:67], v[36:37], off
	global_load_dwordx4 v[68:71], v[36:37], off offset:1024
	global_load_dwordx4 v[32:35], v[36:37], off offset:2048
	s_nop 0
	global_load_dwordx4 v[36:39], v[36:37], off offset:3072
	s_nop 0
	global_load_dwordx4 v[72:75], v[44:45], off
	global_load_dwordx4 v[76:79], v[44:45], off offset:1024
	global_load_dwordx4 v[40:43], v[44:45], off offset:2048
	s_nop 0
	global_load_dwordx4 v[44:47], v[44:45], off offset:3072
	s_nop 0
	global_load_dwordx4 v[80:83], v[52:53], off
	global_load_dwordx4 v[84:87], v[52:53], off offset:1024
	global_load_dwordx4 v[48:51], v[52:53], off offset:2048
	s_nop 0
	global_load_dwordx4 v[52:55], v[52:53], off offset:3072
	s_mov_b32 s8, 6
	v_mov_b32_e32 v244, v102
	v_ashrrev_i32_e32 v245, 31, v102
	v_lshlrev_b64 v[244:245], 7, v[244:245]
	v_lshl_add_u64 v[244:245], v[100:101], 0, v[244:245]
	s_mov_b32 s99, 0
	v_add_u32_e32 v246, 0x10000, v180
	s_branch .LBB0_834
.LBB0_833:
	s_add_i32 s8, s8, 4
	s_cmp_lt_i32 s9, s6
	v_add_u32_e32 v180, 0x1000, v180
	v_add_u32_e32 v246, 0x1000, v246
	s_cbranch_scc0 .LBB0_840
.LBB0_834:
	s_add_i32 s40, s8, -3
	s_min_i32 s9, s40, s7
	s_lshl_b32 s98, s9, 15
	s_waitcnt vmcnt(12)
	v_lshl_add_u64 v[60:61], v[244:245], 0, s[98:99]
	global_load_dwordx4 v[88:91], v[60:61], off
	global_load_dwordx4 v[92:95], v[60:61], off offset:1024
	global_load_dwordx4 v[56:59], v[60:61], off offset:2048
	s_nop 0
	global_load_dwordx4 v[60:63], v[60:61], off offset:3072
	v_add_u32_e32 v103, v178, v98
	s_waitcnt vmcnt(15)
	ds_write_b128 v103, v[64:67]
	s_waitcnt vmcnt(14)
	ds_write_b128 v103, v[68:71] offset:1152
	v_add_u32_e32 v191, v179, v96
	ds_read_b128 v[64:67], v191
	ds_read_b128 v[68:71], v191 offset:64
	s_waitcnt vmcnt(13)
	ds_write_b128 v103, v[32:35]
	s_waitcnt vmcnt(12)
	ds_write_b128 v103, v[36:39] offset:1152
	ds_read_b128 v[32:35], v191
	ds_read_b128 v[36:39], v191 offset:64
	s_waitcnt lgkmcnt(5)
	v_mfma_f32_16x16x32_bf16 v[196:199], v[0:3], v[64:67], 0
	v_mfma_f32_16x16x32_bf16 v[200:203], v[8:11], v[64:67], 0
	s_waitcnt lgkmcnt(4)
	v_mfma_f32_16x16x32_bf16 v[196:199], v[4:7], v[68:71], v[196:199]
	v_mfma_f32_16x16x32_bf16 v[200:203], v[12:15], v[68:71], v[200:203]
	v_mfma_f32_16x16x32_bf16 v[204:207], v[16:19], v[64:67], 0
	s_nop 5
	v_max_f32_e32 v192, 0, v196
	v_fma_f32 v192, v162, v192, 0
	v_max_f32_e32 v195, 0, v197
	v_max_f32_e32 v193, 0, v200
	v_fmac_f32_e32 v192, v163, v195
	v_fma_f32 v193, v166, v193, 0
	v_max_f32_e32 v195, 0, v201
	v_mfma_f32_16x16x32_bf16 v[64:67], v[24:27], v[64:67], 0
	v_fmac_f32_e32 v193, v167, v195
	v_max_f32_e32 v195, 0, v198
	v_fmac_f32_e32 v192, v164, v195
	v_max_f32_e32 v195, 0, v202
	v_mfma_f32_16x16x32_bf16 v[64:67], v[28:31], v[68:71], v[64:67]
	v_fmac_f32_e32 v193, v168, v195
	v_max_f32_e32 v195, 0, v199
	v_mfma_f32_16x16x32_bf16 v[196:199], v[20:23], v[68:71], v[204:207]
	v_fmac_f32_e32 v192, v165, v195
	s_nop 2
	s_nop 0
	v_max_f32_e32 v64, 0, v64
	v_fma_f32 v64, v174, v64, 0
	s_nop 0
	v_max_f32_e32 v68, 0, v196
	v_max_f32_e32 v65, 0, v65
	v_fma_f32 v68, v170, v68, 0
	v_max_f32_e32 v69, 0, v197
	v_fmac_f32_e32 v64, v175, v65
	v_fmac_f32_e32 v68, v171, v69
	v_max_f32_e32 v65, 0, v198
	v_fmac_f32_e32 v68, v172, v65
	v_max_f32_e32 v65, 0, v66
	v_fmac_f32_e32 v64, v176, v65
	v_max_f32_e32 v65, 0, v199
	v_fmac_f32_e32 v68, v173, v65
	v_max_f32_e32 v195, 0, v203
	v_max_f32_e32 v65, 0, v67
	v_fmac_f32_e32 v193, v169, v195
	v_fmac_f32_e32 v64, v177, v65
	v_add_f32_e32 v192, v192, v193
	v_add_f32_e32 v64, v68, v64
	ds_write_b32 v180, v192
	ds_write_b32 v246, v64
	s_waitcnt lgkmcnt(3)
	v_mfma_f32_16x16x32_bf16 v[64:67], v[0:3], v[32:35], 0
	v_mfma_f32_16x16x32_bf16 v[68:71], v[8:11], v[32:35], 0
	s_waitcnt lgkmcnt(2)
	v_mfma_f32_16x16x32_bf16 v[64:67], v[4:7], v[36:39], v[64:67]
	v_mfma_f32_16x16x32_bf16 v[68:71], v[12:15], v[36:39], v[68:71]
	v_mfma_f32_16x16x32_bf16 v[196:199], v[16:19], v[32:35], 0
	s_nop 5
	v_max_f32_e32 v64, 0, v64
	v_fma_f32 v192, v162, v64, 0
	v_max_f32_e32 v64, 0, v68
	v_fma_f32 v68, v166, v64, 0
	v_max_f32_e32 v64, 0, v65
	v_fmac_f32_e32 v192, v163, v64
	v_max_f32_e32 v64, 0, v69
	v_fmac_f32_e32 v68, v167, v64
	v_max_f32_e32 v64, 0, v66
	v_fmac_f32_e32 v192, v164, v64
	v_mfma_f32_16x16x32_bf16 v[32:35], v[24:27], v[32:35], 0
	v_max_f32_e32 v64, 0, v70
	v_fmac_f32_e32 v68, v168, v64
	v_max_f32_e32 v64, 0, v67
	v_fmac_f32_e32 v192, v165, v64
	v_mfma_f32_16x16x32_bf16 v[32:35], v[28:31], v[36:39], v[32:35]
	v_max_f32_e32 v69, 0, v71
	v_fmac_f32_e32 v68, v169, v69
	v_add_f32_e32 v68, v192, v68
	v_mfma_f32_16x16x32_bf16 v[64:67], v[20:23], v[36:39], v[196:199]
	ds_write_b32 v180, v68 offset:64
	s_nop 2
	v_max_f32_e32 v32, 0, v32
	v_fma_f32 v32, v174, v32, 0
	s_nop 1
	v_max_f32_e32 v36, 0, v64
	v_max_f32_e32 v33, 0, v33
	v_fma_f32 v36, v170, v36, 0
	v_max_f32_e32 v37, 0, v65
	v_fmac_f32_e32 v32, v175, v33
	v_fmac_f32_e32 v36, v171, v37
	v_max_f32_e32 v33, 0, v66
	v_fmac_f32_e32 v36, v172, v33
	v_max_f32_e32 v33, 0, v34
	v_fmac_f32_e32 v32, v176, v33
	v_max_f32_e32 v33, 0, v67
	v_fmac_f32_e32 v36, v173, v33
	v_max_f32_e32 v33, 0, v35
	v_fmac_f32_e32 v32, v177, v33
	v_add_f32_e32 v32, v36, v32
	ds_write_b32 v246, v32 offset:64
	s_add_i32 s9, s8, -2
	s_min_i32 s57, s9, s7
	s_lshl_b32 s98, s57, 15
	v_lshl_add_u64 v[36:37], v[244:245], 0, s[98:99]
	global_load_dwordx4 v[64:67], v[36:37], off
	global_load_dwordx4 v[68:71], v[36:37], off offset:1024
	global_load_dwordx4 v[32:35], v[36:37], off offset:2048
	s_nop 0
	global_load_dwordx4 v[36:39], v[36:37], off offset:3072
	s_add_i32 s57, s8, -5
	s_cmp_ge_i32 s57, s6
	s_cbranch_scc1 .LBB0_836
	s_waitcnt vmcnt(15)
	ds_write_b128 v103, v[72:75]
	s_waitcnt vmcnt(14)
	ds_write_b128 v103, v[76:79] offset:1152
	ds_read_b128 v[72:75], v191
	ds_read_b128 v[76:79], v191 offset:64
	s_waitcnt vmcnt(13)
	ds_write_b128 v103, v[40:43]
	s_waitcnt vmcnt(12)
	ds_write_b128 v103, v[44:47] offset:1152
	ds_read_b128 v[40:43], v191
	ds_read_b128 v[44:47], v191 offset:64
	s_waitcnt lgkmcnt(5)
	v_mfma_f32_16x16x32_bf16 v[196:199], v[0:3], v[72:75], 0
	v_mfma_f32_16x16x32_bf16 v[200:203], v[8:11], v[72:75], 0
	s_waitcnt lgkmcnt(4)
	v_mfma_f32_16x16x32_bf16 v[196:199], v[4:7], v[76:79], v[196:199]
	v_mfma_f32_16x16x32_bf16 v[200:203], v[12:15], v[76:79], v[200:203]
	v_mfma_f32_16x16x32_bf16 v[204:207], v[16:19], v[72:75], 0
	s_nop 5
	v_max_f32_e32 v192, 0, v196
	v_fma_f32 v192, v162, v192, 0
	v_max_f32_e32 v195, 0, v197
	v_max_f32_e32 v193, 0, v200
	v_fmac_f32_e32 v192, v163, v195
	v_fma_f32 v193, v166, v193, 0
	v_max_f32_e32 v195, 0, v201
	v_mfma_f32_16x16x32_bf16 v[72:75], v[24:27], v[72:75], 0
	v_fmac_f32_e32 v193, v167, v195
	v_max_f32_e32 v195, 0, v198
	v_fmac_f32_e32 v192, v164, v195
	v_max_f32_e32 v195, 0, v202
	v_mfma_f32_16x16x32_bf16 v[72:75], v[28:31], v[76:79], v[72:75]
	v_fmac_f32_e32 v193, v168, v195
	v_max_f32_e32 v195, 0, v199
	v_mfma_f32_16x16x32_bf16 v[196:199], v[20:23], v[76:79], v[204:207]
	v_fmac_f32_e32 v192, v165, v195
	s_nop 2
	s_nop 0
	v_max_f32_e32 v72, 0, v72
	v_fma_f32 v72, v174, v72, 0
	s_nop 0
	v_max_f32_e32 v76, 0, v196
	v_max_f32_e32 v73, 0, v73
	v_fma_f32 v76, v170, v76, 0
	v_max_f32_e32 v77, 0, v197
	v_fmac_f32_e32 v72, v175, v73
	v_fmac_f32_e32 v76, v171, v77
	v_max_f32_e32 v73, 0, v198
	v_fmac_f32_e32 v76, v172, v73
	v_max_f32_e32 v73, 0, v74
	v_fmac_f32_e32 v72, v176, v73
	v_max_f32_e32 v73, 0, v199
	v_fmac_f32_e32 v76, v173, v73
	v_max_f32_e32 v195, 0, v203
	v_max_f32_e32 v73, 0, v75
	v_fmac_f32_e32 v193, v169, v195
	v_fmac_f32_e32 v72, v177, v73
	v_add_f32_e32 v192, v192, v193
	v_add_f32_e32 v72, v76, v72
	ds_write_b32 v180, v192 offset:1024
	ds_write_b32 v246, v72 offset:1024
	s_waitcnt lgkmcnt(3)
	v_mfma_f32_16x16x32_bf16 v[72:75], v[0:3], v[40:43], 0
	v_mfma_f32_16x16x32_bf16 v[76:79], v[8:11], v[40:43], 0
	s_waitcnt lgkmcnt(2)
	v_mfma_f32_16x16x32_bf16 v[72:75], v[4:7], v[44:47], v[72:75]
	v_mfma_f32_16x16x32_bf16 v[76:79], v[12:15], v[44:47], v[76:79]
	v_mfma_f32_16x16x32_bf16 v[196:199], v[16:19], v[40:43], 0
	s_nop 5
	v_max_f32_e32 v72, 0, v72
	v_fma_f32 v192, v162, v72, 0
	v_max_f32_e32 v72, 0, v76
	v_fma_f32 v76, v166, v72, 0
	v_max_f32_e32 v72, 0, v73
	v_fmac_f32_e32 v192, v163, v72
	v_max_f32_e32 v72, 0, v77
	v_fmac_f32_e32 v76, v167, v72
	v_max_f32_e32 v72, 0, v74
	v_fmac_f32_e32 v192, v164, v72
	v_mfma_f32_16x16x32_bf16 v[40:43], v[24:27], v[40:43], 0
	v_max_f32_e32 v72, 0, v78
	v_fmac_f32_e32 v76, v168, v72
	v_max_f32_e32 v72, 0, v75
	v_fmac_f32_e32 v192, v165, v72
	v_mfma_f32_16x16x32_bf16 v[40:43], v[28:31], v[44:47], v[40:43]
	v_max_f32_e32 v77, 0, v79
	v_fmac_f32_e32 v76, v169, v77
	v_add_f32_e32 v76, v192, v76
	v_mfma_f32_16x16x32_bf16 v[72:75], v[20:23], v[44:47], v[196:199]
	ds_write_b32 v180, v76 offset:1088
	s_nop 2
	v_max_f32_e32 v40, 0, v40
	v_fma_f32 v40, v174, v40, 0
	s_nop 1
	v_max_f32_e32 v44, 0, v72
	v_max_f32_e32 v41, 0, v41
	v_fma_f32 v44, v170, v44, 0
	v_max_f32_e32 v45, 0, v73
	v_fmac_f32_e32 v40, v175, v41
	v_fmac_f32_e32 v44, v171, v45
	v_max_f32_e32 v41, 0, v74
	v_fmac_f32_e32 v44, v172, v41
	v_max_f32_e32 v41, 0, v42
	v_fmac_f32_e32 v40, v176, v41
	v_max_f32_e32 v41, 0, v75
	v_fmac_f32_e32 v44, v173, v41
	v_max_f32_e32 v41, 0, v43
	v_fmac_f32_e32 v40, v177, v41
	v_add_f32_e32 v40, v44, v40
	ds_write_b32 v246, v40 offset:1088
.LBB0_836:
	s_add_i32 s57, s8, -1
	s_min_i32 s57, s57, s7
	s_lshl_b32 s98, s57, 15
	s_waitcnt vmcnt(12)
	v_lshl_add_u64 v[44:45], v[244:245], 0, s[98:99]
	global_load_dwordx4 v[72:75], v[44:45], off
	global_load_dwordx4 v[76:79], v[44:45], off offset:1024
	global_load_dwordx4 v[40:43], v[44:45], off offset:2048
	s_nop 0
	global_load_dwordx4 v[44:47], v[44:45], off offset:3072
	s_add_i32 s57, s8, -4
	s_cmp_ge_i32 s57, s6
	s_cbranch_scc1 .LBB0_838
	s_waitcnt vmcnt(15)
	ds_write_b128 v103, v[80:83]
	s_waitcnt vmcnt(14)
	ds_write_b128 v103, v[84:87] offset:1152
	ds_read_b128 v[80:83], v191
	ds_read_b128 v[84:87], v191 offset:64
	s_waitcnt vmcnt(13)
	ds_write_b128 v103, v[48:51]
	s_waitcnt vmcnt(12)
	ds_write_b128 v103, v[52:55] offset:1152
	ds_read_b128 v[48:51], v191
	ds_read_b128 v[52:55], v191 offset:64
	s_waitcnt lgkmcnt(5)
	v_mfma_f32_16x16x32_bf16 v[196:199], v[0:3], v[80:83], 0
	v_mfma_f32_16x16x32_bf16 v[200:203], v[8:11], v[80:83], 0
	s_waitcnt lgkmcnt(4)
	v_mfma_f32_16x16x32_bf16 v[196:199], v[4:7], v[84:87], v[196:199]
	v_mfma_f32_16x16x32_bf16 v[200:203], v[12:15], v[84:87], v[200:203]
	v_mfma_f32_16x16x32_bf16 v[204:207], v[16:19], v[80:83], 0
	s_nop 5
	v_max_f32_e32 v192, 0, v196
	v_fma_f32 v192, v162, v192, 0
	v_max_f32_e32 v195, 0, v197
	v_max_f32_e32 v193, 0, v200
	v_fmac_f32_e32 v192, v163, v195
	v_fma_f32 v193, v166, v193, 0
	v_max_f32_e32 v195, 0, v201
	v_mfma_f32_16x16x32_bf16 v[80:83], v[24:27], v[80:83], 0
	v_fmac_f32_e32 v193, v167, v195
	v_max_f32_e32 v195, 0, v198
	v_fmac_f32_e32 v192, v164, v195
	v_max_f32_e32 v195, 0, v202
	v_mfma_f32_16x16x32_bf16 v[80:83], v[28:31], v[84:87], v[80:83]
	v_fmac_f32_e32 v193, v168, v195
	v_max_f32_e32 v195, 0, v199
	v_mfma_f32_16x16x32_bf16 v[196:199], v[20:23], v[84:87], v[204:207]
	v_fmac_f32_e32 v192, v165, v195
	s_nop 2
	s_nop 0
	v_max_f32_e32 v80, 0, v80
	v_fma_f32 v80, v174, v80, 0
	s_nop 0
	v_max_f32_e32 v84, 0, v196
	v_max_f32_e32 v81, 0, v81
	v_fma_f32 v84, v170, v84, 0
	v_max_f32_e32 v85, 0, v197
	v_fmac_f32_e32 v80, v175, v81
	v_fmac_f32_e32 v84, v171, v85
	v_max_f32_e32 v81, 0, v198
	v_fmac_f32_e32 v84, v172, v81
	v_max_f32_e32 v81, 0, v82
	v_fmac_f32_e32 v80, v176, v81
	v_max_f32_e32 v81, 0, v199
	v_fmac_f32_e32 v84, v173, v81
	v_max_f32_e32 v195, 0, v203
	v_max_f32_e32 v81, 0, v83
	v_fmac_f32_e32 v193, v169, v195
	v_fmac_f32_e32 v80, v177, v81
	v_add_f32_e32 v192, v192, v193
	v_add_f32_e32 v80, v84, v80
	ds_write_b32 v180, v192 offset:2048
	ds_write_b32 v246, v80 offset:2048
	s_waitcnt lgkmcnt(3)
	v_mfma_f32_16x16x32_bf16 v[80:83], v[0:3], v[48:51], 0
	v_mfma_f32_16x16x32_bf16 v[84:87], v[8:11], v[48:51], 0
	s_waitcnt lgkmcnt(2)
	v_mfma_f32_16x16x32_bf16 v[80:83], v[4:7], v[52:55], v[80:83]
	v_mfma_f32_16x16x32_bf16 v[84:87], v[12:15], v[52:55], v[84:87]
	v_mfma_f32_16x16x32_bf16 v[196:199], v[16:19], v[48:51], 0
	s_nop 5
	v_max_f32_e32 v80, 0, v80
	v_fma_f32 v192, v162, v80, 0
	v_max_f32_e32 v80, 0, v84
	v_fma_f32 v84, v166, v80, 0
	v_max_f32_e32 v80, 0, v81
	v_fmac_f32_e32 v192, v163, v80
	v_max_f32_e32 v80, 0, v85
	v_fmac_f32_e32 v84, v167, v80
	v_max_f32_e32 v80, 0, v82
	v_fmac_f32_e32 v192, v164, v80
	v_mfma_f32_16x16x32_bf16 v[48:51], v[24:27], v[48:51], 0
	v_max_f32_e32 v80, 0, v86
	v_fmac_f32_e32 v84, v168, v80
	v_max_f32_e32 v80, 0, v83
	v_fmac_f32_e32 v192, v165, v80
	v_mfma_f32_16x16x32_bf16 v[48:51], v[28:31], v[52:55], v[48:51]
	v_max_f32_e32 v85, 0, v87
	v_fmac_f32_e32 v84, v169, v85
	v_add_f32_e32 v84, v192, v84
	v_mfma_f32_16x16x32_bf16 v[80:83], v[20:23], v[52:55], v[196:199]
	ds_write_b32 v180, v84 offset:2112
	s_nop 2
	v_max_f32_e32 v48, 0, v48
	v_fma_f32 v48, v174, v48, 0
	s_nop 1
	v_max_f32_e32 v52, 0, v80
	v_max_f32_e32 v49, 0, v49
	v_fma_f32 v52, v170, v52, 0
	v_max_f32_e32 v53, 0, v81
	v_fmac_f32_e32 v48, v175, v49
	v_fmac_f32_e32 v52, v171, v53
	v_max_f32_e32 v49, 0, v82
	v_fmac_f32_e32 v52, v172, v49
	v_max_f32_e32 v49, 0, v50
	v_fmac_f32_e32 v48, v176, v49
	v_max_f32_e32 v49, 0, v83
	v_fmac_f32_e32 v52, v173, v49
	v_max_f32_e32 v49, 0, v51
	v_fmac_f32_e32 v48, v177, v49
	v_add_f32_e32 v48, v52, v48
	ds_write_b32 v246, v48 offset:2112
.LBB0_838:
	s_min_i32 s57, s8, s7
	s_lshl_b32 s98, s57, 15
	s_cmp_ge_i32 s40, s6
	s_waitcnt vmcnt(12)
	v_lshl_add_u64 v[52:53], v[244:245], 0, s[98:99]
	global_load_dwordx4 v[80:83], v[52:53], off
	global_load_dwordx4 v[84:87], v[52:53], off offset:1024
	global_load_dwordx4 v[48:51], v[52:53], off offset:2048
	s_nop 0
	global_load_dwordx4 v[52:55], v[52:53], off offset:3072
	s_cbranch_scc1 .LBB0_833
	s_waitcnt vmcnt(15)
	ds_write_b128 v103, v[88:91]
	s_waitcnt vmcnt(14)
	ds_write_b128 v103, v[92:95] offset:1152
	ds_read_b128 v[88:91], v191
	ds_read_b128 v[92:95], v191 offset:64
	s_waitcnt vmcnt(13)
	ds_write_b128 v103, v[56:59]
	s_waitcnt vmcnt(12)
	ds_write_b128 v103, v[60:63] offset:1152
	ds_read_b128 v[56:59], v191
	ds_read_b128 v[60:63], v191 offset:64
	s_waitcnt lgkmcnt(5)
	v_mfma_f32_16x16x32_bf16 v[196:199], v[0:3], v[88:91], 0
	v_mfma_f32_16x16x32_bf16 v[200:203], v[8:11], v[88:91], 0
	s_waitcnt lgkmcnt(4)
	v_mfma_f32_16x16x32_bf16 v[196:199], v[4:7], v[92:95], v[196:199]
	v_mfma_f32_16x16x32_bf16 v[200:203], v[12:15], v[92:95], v[200:203]
	v_mfma_f32_16x16x32_bf16 v[204:207], v[16:19], v[88:91], 0
	s_nop 5
	v_max_f32_e32 v192, 0, v196
	v_fma_f32 v192, v162, v192, 0
	v_max_f32_e32 v195, 0, v197
	v_max_f32_e32 v193, 0, v200
	v_fmac_f32_e32 v192, v163, v195
	v_fma_f32 v193, v166, v193, 0
	v_max_f32_e32 v195, 0, v201
	v_mfma_f32_16x16x32_bf16 v[88:91], v[24:27], v[88:91], 0
	v_fmac_f32_e32 v193, v167, v195
	v_max_f32_e32 v195, 0, v198
	v_fmac_f32_e32 v192, v164, v195
	v_max_f32_e32 v195, 0, v202
	v_mfma_f32_16x16x32_bf16 v[88:91], v[28:31], v[92:95], v[88:91]
	v_fmac_f32_e32 v193, v168, v195
	v_max_f32_e32 v195, 0, v199
	v_mfma_f32_16x16x32_bf16 v[196:199], v[20:23], v[92:95], v[204:207]
	v_fmac_f32_e32 v192, v165, v195
	s_nop 2
	s_nop 0
	v_max_f32_e32 v88, 0, v88
	v_fma_f32 v88, v174, v88, 0
	s_nop 0
	v_max_f32_e32 v92, 0, v196
	v_max_f32_e32 v89, 0, v89
	v_fma_f32 v92, v170, v92, 0
	v_max_f32_e32 v93, 0, v197
	v_fmac_f32_e32 v88, v175, v89
	v_fmac_f32_e32 v92, v171, v93
	v_max_f32_e32 v89, 0, v198
	v_fmac_f32_e32 v92, v172, v89
	v_max_f32_e32 v89, 0, v90
	v_fmac_f32_e32 v88, v176, v89
	v_max_f32_e32 v89, 0, v199
	v_fmac_f32_e32 v92, v173, v89
	v_max_f32_e32 v195, 0, v203
	v_max_f32_e32 v89, 0, v91
	v_fmac_f32_e32 v193, v169, v195
	v_fmac_f32_e32 v88, v177, v89
	v_add_f32_e32 v192, v192, v193
	v_add_f32_e32 v88, v92, v88
	ds_write_b32 v180, v192 offset:3072
	ds_write_b32 v246, v88 offset:3072
	s_waitcnt lgkmcnt(3)
	v_mfma_f32_16x16x32_bf16 v[88:91], v[0:3], v[56:59], 0
	v_mfma_f32_16x16x32_bf16 v[92:95], v[8:11], v[56:59], 0
	s_waitcnt lgkmcnt(2)
	v_mfma_f32_16x16x32_bf16 v[88:91], v[4:7], v[60:63], v[88:91]
	v_mfma_f32_16x16x32_bf16 v[92:95], v[12:15], v[60:63], v[92:95]
	v_mfma_f32_16x16x32_bf16 v[196:199], v[16:19], v[56:59], 0
	s_nop 5
	v_max_f32_e32 v88, 0, v88
	v_fma_f32 v103, v162, v88, 0
	v_max_f32_e32 v88, 0, v92
	v_fma_f32 v92, v166, v88, 0
	v_max_f32_e32 v88, 0, v89
	v_fmac_f32_e32 v103, v163, v88
	v_max_f32_e32 v88, 0, v93
	v_fmac_f32_e32 v92, v167, v88
	v_max_f32_e32 v88, 0, v90
	v_fmac_f32_e32 v103, v164, v88
	v_mfma_f32_16x16x32_bf16 v[56:59], v[24:27], v[56:59], 0
	v_max_f32_e32 v88, 0, v94
	v_fmac_f32_e32 v92, v168, v88
	v_max_f32_e32 v88, 0, v91
	v_fmac_f32_e32 v103, v165, v88
	v_mfma_f32_16x16x32_bf16 v[56:59], v[28:31], v[60:63], v[56:59]
	v_max_f32_e32 v93, 0, v95
	v_fmac_f32_e32 v92, v169, v93
	v_add_f32_e32 v92, v103, v92
	v_mfma_f32_16x16x32_bf16 v[88:91], v[20:23], v[60:63], v[196:199]
	ds_write_b32 v180, v92 offset:3136
	s_nop 2
	v_max_f32_e32 v56, 0, v56
	v_fma_f32 v56, v174, v56, 0
	s_nop 1
	v_max_f32_e32 v60, 0, v88
	v_max_f32_e32 v57, 0, v57
	v_fma_f32 v60, v170, v60, 0
	v_max_f32_e32 v61, 0, v89
	v_fmac_f32_e32 v56, v175, v57
	v_fmac_f32_e32 v60, v171, v61
	v_max_f32_e32 v57, 0, v90
	v_fmac_f32_e32 v60, v172, v57
	v_max_f32_e32 v57, 0, v58
	v_fmac_f32_e32 v56, v176, v57
	v_max_f32_e32 v57, 0, v91
	v_fmac_f32_e32 v60, v173, v57
	v_max_f32_e32 v57, 0, v59
	v_fmac_f32_e32 v56, v177, v57
	v_add_f32_e32 v56, v60, v56
	ds_write_b32 v246, v56 offset:3136
	s_branch .LBB0_833
